# v25 plus diff-attention near-diagonal (general) ALiBi bias block packed f32 ops split into scalar ops
# speedup vs baseline: 1.0115x; 1.0014x over previous
; template <int DQK, bool ALIBI>
; DI void attn_pass(const u16* __restrict__ Qp, int ldq, const u16* __restrict__ Kp, int ldk, const u16* __restrict__ VTp,
;                   int seq_start, int kt_lo, int kt_hi, int q0, float slope2, f32x16 (&O)[4], float& lsum, char* lds) {
;     ...
;     if (ALIBI) {
;       const float dq = qpos - (float)kb;
;       if (kb + 64 <= qw0 || kb > qw0 + 31) {
;         const float sl = (kb + 64 <= qw0) ? slope2 : -slope2;
;         const float T0 = -sl * dq, T1 = T0 + 32.f * sl;
; #pragma unroll
;         for (int i = 0; i < 16; ++i) {
;           S0[i] = fmaf(sl, (float)((i & 3) + 8 * (i >> 2)), T0);
;           S1[i] = fmaf(sl, (float)((i & 3) + 8 * (i >> 2)), T1);
;         }
;       } else {
; #pragma unroll
;         for (int i = 0; i < 16; ++i) {
;           S0[i] = -slope2 * fabsf(dq - (float)((i & 3) + 8 * (i >> 2)));
;           S1[i] = -slope2 * fabsf(dq - 32.f - (float)((i & 3) + 8 * (i >> 2)));
;         }
;       }
.LBB0_1149:
	v_cvt_f32_u32_e32 v66, s89
	s_add_i32 s88, s89, 64
	v_cmp_gt_i32_e64 s[44:45], s88, v129
	v_cmp_le_i32_e64 s[46:47], s89, v155
	v_cmp_le_i32_e32 vcc, s88, v129
	v_sub_f32_e32 v144, v154, v66
	s_and_b64 s[6:7], s[44:45], s[46:47]
	s_and_saveexec_b64 s[44:45], s[6:7]
	s_xor_b64 s[6:7], exec, s[44:45]
	s_cbranch_execz .LBB0_1151
	v_add_f32_e32 v68, s38, v144
	v_add_f32_e32 v69, s39, v144
	v_add_f32_e32 v84, s74, v144
	v_add_f32_e32 v85, s75, v144
	v_add_f32_e32 v67, -1.0, v144
	v_add_f32_e32 v66, 0xc2000000, v144
	v_add_f32_e32 v72, s18, v144
	v_add_f32_e32 v73, s19, v144
	v_add_f32_e32 v76, s4, v144
	v_add_f32_e32 v77, s5, v144
	v_add_f32_e32 v82, s24, v144
	v_add_f32_e32 v83, s25, v144
	v_add_f32_e32 v86, s22, v144
	v_add_f32_e32 v87, s23, v144
	v_and_b32_e32 v69, 0x7fffffff, v69
	v_and_b32_e32 v68, 0x7fffffff, v68
	v_and_b32_e32 v85, 0x7fffffff, v85
	v_and_b32_e32 v84, 0x7fffffff, v84
	v_mov_b32_e32 v131, v130
	v_add_f32_e32 v166, -1.0, v66
	v_add_f32_e32 v70, s38, v66
	v_add_f32_e32 v71, s39, v66
	v_add_f32_e32 v74, s18, v66
	v_add_f32_e32 v75, s19, v66
	v_add_f32_e32 v78, s4, v66
	v_add_f32_e32 v79, s5, v66
	v_add_f32_e32 v80, s34, v144
	v_add_f32_e32 v81, s35, v144
	v_add_f32_e32 v160, s34, v66
	v_add_f32_e32 v161, s35, v66
	v_add_f32_e32 v162, s24, v66
	v_add_f32_e32 v163, s25, v66
	v_add_f32_e32 v164, s74, v66
	v_add_f32_e32 v165, s75, v66
	v_and_b32_e32 v73, 0x7fffffff, v73
	v_and_b32_e32 v72, 0x7fffffff, v72
	v_and_b32_e32 v77, 0x7fffffff, v77
	v_and_b32_e32 v76, 0x7fffffff, v76
	v_and_b32_e32 v83, 0x7fffffff, v83
	v_and_b32_e32 v82, 0x7fffffff, v82
	v_and_b32_e32 v87, 0x7fffffff, v87
	v_and_b32_e32 v86, 0x7fffffff, v86
	v_and_b32_e32 v144, 0x7fffffff, v144
	v_and_b32_e32 v145, 0x7fffffff, v67
	v_mul_f32_e32 v94, v84, v130
	v_mul_f32_e32 v95, v85, v131
	v_mul_f32_e32 v84, v68, v130
	v_mul_f32_e32 v85, v69, v131
	v_add_f32_e32 v68, s22, v66
	v_add_f32_e32 v69, s23, v66
	v_and_b32_e32 v81, 0x7fffffff, v81
	v_and_b32_e32 v80, 0x7fffffff, v80
	v_mul_f32_e32 v96, v86, v130
	v_mul_f32_e32 v97, v87, v131
	v_mul_f32_e32 v92, v82, v130
	v_mul_f32_e32 v93, v83, v131
	v_mul_f32_e32 v88, v76, v130
	v_mul_f32_e32 v89, v77, v131
	v_mul_f32_e32 v86, v72, v130
	v_mul_f32_e32 v87, v73, v131
	v_mul_f32_e32 v82, v144, v134
	v_mul_f32_e32 v83, v145, v135
	v_and_b32_e32 v145, 0x7fffffff, v71
	v_and_b32_e32 v144, 0x7fffffff, v70
	v_and_b32_e32 v71, 0x7fffffff, v75
	v_and_b32_e32 v70, 0x7fffffff, v74
	v_and_b32_e32 v73, 0x7fffffff, v79
	v_and_b32_e32 v72, 0x7fffffff, v78
	v_and_b32_e32 v75, 0x7fffffff, v161
	v_and_b32_e32 v74, 0x7fffffff, v160
	v_and_b32_e32 v77, 0x7fffffff, v163
	v_and_b32_e32 v76, 0x7fffffff, v162
	v_and_b32_e32 v79, 0x7fffffff, v165
	v_and_b32_e32 v78, 0x7fffffff, v164
	v_and_b32_e32 v69, 0x7fffffff, v69
	v_and_b32_e32 v68, 0x7fffffff, v68
	v_and_b32_e32 v66, 0x7fffffff, v66
	v_and_b32_e32 v67, 0x7fffffff, v166
	v_mul_f32_e32 v90, v80, v130
	v_mul_f32_e32 v91, v81, v131
	v_mul_f32_e32 v80, v68, v130
	v_mul_f32_e32 v81, v69, v131
	v_mul_f32_e32 v78, v78, v130
	v_mul_f32_e32 v79, v79, v131
	v_mul_f32_e32 v76, v76, v130
	v_mul_f32_e32 v77, v77, v131
	v_mul_f32_e32 v74, v74, v130
	v_mul_f32_e32 v75, v75, v131
	v_mul_f32_e32 v72, v72, v130
	v_mul_f32_e32 v73, v73, v131
	v_mul_f32_e32 v70, v70, v130
	v_mul_f32_e32 v71, v71, v131
	v_mul_f32_e32 v68, v144, v130
	v_mul_f32_e32 v69, v145, v131
	v_mul_f32_e32 v66, v66, v134
	v_mul_f32_e32 v67, v67, v135
